# attention: exp/sub/cvt of score group g+1 and the row-sum tree interleaved with the PV MFMAs of group g (on top of deferred rescale)
# speedup vs baseline: 1.0044x; 1.0044x over previous
.LBB0_203:
	v_sub_f32_e32 v96, v96, v234
	v_sub_f32_e32 v97, v97, v234
	v_sub_f32_e32 v98, v98, v234
	v_sub_f32_e32 v99, v99, v234
	v_sub_f32_e32 v100, v100, v234
	v_sub_f32_e32 v101, v101, v234
	v_sub_f32_e32 v102, v102, v234
	v_sub_f32_e32 v103, v103, v234
	v_exp_f32_e32 v96, v96
	v_exp_f32_e32 v97, v97
	v_exp_f32_e32 v98, v98
	v_exp_f32_e32 v99, v99
	v_exp_f32_e32 v100, v100
	v_exp_f32_e32 v101, v101
	v_exp_f32_e32 v102, v102
	v_exp_f32_e32 v103, v103
	v_sub_f32_e32 v104, v104, v234
	v_sub_f32_e32 v105, v105, v234
	v_sub_f32_e32 v106, v106, v234
	v_sub_f32_e32 v107, v107, v234
	v_sub_f32_e32 v108, v108, v234
	v_sub_f32_e32 v109, v109, v234
	v_sub_f32_e32 v110, v110, v234
	v_sub_f32_e32 v111, v111, v234
	s_setprio 1
	ds_read_b128 v[222:225], v209
	ds_read_b128 v[240:243], v209 offset:4608
	ds_read_b128 v[244:247], v209 offset:9216
	ds_read_b128 v[248:251], v209 offset:13824
	v_cvt_pk_bf16_f32 v236, v96, v97
	v_cvt_pk_bf16_f32 v237, v98, v99
	v_cvt_pk_bf16_f32 v238, v100, v101
	v_cvt_pk_bf16_f32 v239, v102, v103
	s_waitcnt lgkmcnt(3)
	s_nop 0
	v_mfma_f32_32x32x16_bf16 v[48:63], v[222:225], v[236:239], v[48:63]
	ds_read_b128 v[222:225], v209 offset:32
	v_exp_f32_e32 v104, v104
	v_exp_f32_e32 v105, v105
	v_sub_f32_e32 v112, v112, v234
	v_sub_f32_e32 v113, v113, v234
	s_waitcnt lgkmcnt(3)
	v_mfma_f32_32x32x16_bf16 v[32:47], v[240:243], v[236:239], v[32:47]
	ds_read_b128 v[240:243], v209 offset:4640
	v_exp_f32_e32 v106, v106
	v_exp_f32_e32 v107, v107
	v_sub_f32_e32 v114, v114, v234
	v_sub_f32_e32 v115, v115, v234
	s_waitcnt lgkmcnt(3)
	v_mfma_f32_32x32x16_bf16 v[16:31], v[244:247], v[236:239], v[16:31]
	ds_read_b128 v[244:247], v209 offset:9248
	v_exp_f32_e32 v108, v108
	v_exp_f32_e32 v109, v109
	v_sub_f32_e32 v116, v116, v234
	v_sub_f32_e32 v117, v117, v234
	s_waitcnt lgkmcnt(3)
	v_mfma_f32_32x32x16_bf16 v[0:15], v[248:251], v[236:239], v[0:15]
	ds_read_b128 v[248:251], v209 offset:13856
	v_exp_f32_e32 v110, v110
	v_exp_f32_e32 v111, v111
	v_sub_f32_e32 v118, v118, v234
	v_sub_f32_e32 v119, v119, v234
	v_cvt_pk_bf16_f32 v236, v104, v105
	v_cvt_pk_bf16_f32 v237, v106, v107
	v_cvt_pk_bf16_f32 v238, v108, v109
	v_cvt_pk_bf16_f32 v239, v110, v111
	s_waitcnt lgkmcnt(3)
	s_nop 0
	v_mfma_f32_32x32x16_bf16 v[48:63], v[222:225], v[236:239], v[48:63]
	ds_read_b128 v[222:225], v209 offset:64
	v_exp_f32_e32 v112, v112
	v_exp_f32_e32 v113, v113
	v_sub_f32_e32 v120, v120, v234
	v_sub_f32_e32 v121, v121, v234
	s_waitcnt lgkmcnt(3)
	v_mfma_f32_32x32x16_bf16 v[32:47], v[240:243], v[236:239], v[32:47]
	ds_read_b128 v[240:243], v209 offset:4672
	v_exp_f32_e32 v114, v114
	v_exp_f32_e32 v115, v115
	v_sub_f32_e32 v122, v122, v234
	v_sub_f32_e32 v123, v123, v234
	s_waitcnt lgkmcnt(3)
	v_mfma_f32_32x32x16_bf16 v[16:31], v[244:247], v[236:239], v[16:31]
	ds_read_b128 v[244:247], v209 offset:9280
	v_exp_f32_e32 v116, v116
	v_exp_f32_e32 v117, v117
	v_sub_f32_e32 v124, v124, v234
	v_sub_f32_e32 v125, v125, v234
	s_waitcnt lgkmcnt(3)
	v_mfma_f32_32x32x16_bf16 v[0:15], v[248:251], v[236:239], v[0:15]
	ds_read_b128 v[248:251], v209 offset:13888
	v_exp_f32_e32 v118, v118
	v_exp_f32_e32 v119, v119
	v_sub_f32_e32 v126, v126, v234
	v_sub_f32_e32 v127, v127, v234
	v_cvt_pk_bf16_f32 v236, v112, v113
	v_cvt_pk_bf16_f32 v237, v114, v115
	v_cvt_pk_bf16_f32 v238, v116, v117
	v_cvt_pk_bf16_f32 v239, v118, v119
	s_waitcnt lgkmcnt(3)
	s_nop 0
	v_mfma_f32_32x32x16_bf16 v[48:63], v[222:225], v[236:239], v[48:63]
	ds_read_b128 v[222:225], v209 offset:96
	v_exp_f32_e32 v120, v120
	v_exp_f32_e32 v121, v121
	s_waitcnt lgkmcnt(3)
	v_mfma_f32_32x32x16_bf16 v[32:47], v[240:243], v[236:239], v[32:47]
	ds_read_b128 v[240:243], v209 offset:4704
	v_exp_f32_e32 v122, v122
	v_exp_f32_e32 v123, v123
	s_waitcnt lgkmcnt(3)
	v_mfma_f32_32x32x16_bf16 v[16:31], v[244:247], v[236:239], v[16:31]
	ds_read_b128 v[244:247], v209 offset:9312
	v_exp_f32_e32 v124, v124
	v_exp_f32_e32 v125, v125
	s_waitcnt lgkmcnt(3)
	v_mfma_f32_32x32x16_bf16 v[0:15], v[248:251], v[236:239], v[0:15]
	ds_read_b128 v[248:251], v209 offset:13920
	v_exp_f32_e32 v126, v126
	v_exp_f32_e32 v127, v127
	v_cvt_pk_bf16_f32 v236, v120, v121
	v_cvt_pk_bf16_f32 v237, v122, v123
	v_cvt_pk_bf16_f32 v238, v124, v125
	v_cvt_pk_bf16_f32 v239, v126, v127
	s_waitcnt lgkmcnt(3)
	s_nop 0
	v_mfma_f32_32x32x16_bf16 v[48:63], v[222:225], v[236:239], v[48:63]
	v_pk_add_f32 v[100:101], v[100:101], v[116:117]
	v_pk_add_f32 v[96:97], v[96:97], v[112:113]
	v_pk_add_f32 v[102:103], v[102:103], v[118:119]
	v_pk_add_f32 v[98:99], v[98:99], v[114:115]
	v_pk_add_f32 v[106:107], v[106:107], v[122:123]
	s_waitcnt lgkmcnt(2)
	v_mfma_f32_32x32x16_bf16 v[32:47], v[240:243], v[236:239], v[32:47]
	v_pk_add_f32 v[104:105], v[104:105], v[120:121]
	v_pk_add_f32 v[102:103], v[98:99], v[102:103]
	v_pk_add_f32 v[100:101], v[96:97], v[100:101]
	v_pk_add_f32 v[108:109], v[108:109], v[124:125]
	v_pk_add_f32 v[110:111], v[110:111], v[126:127]
	s_waitcnt lgkmcnt(1)
	v_mfma_f32_32x32x16_bf16 v[16:31], v[244:247], v[236:239], v[16:31]
	v_pk_add_f32 v[104:105], v[104:105], v[100:101]
	v_pk_add_f32 v[106:107], v[106:107], v[102:103]
	v_pk_add_f32 v[108:109], v[108:109], v[104:105]
	v_pk_add_f32 v[110:111], v[110:111], v[106:107]
	s_waitcnt lgkmcnt(0)
	v_mfma_f32_32x32x16_bf16 v[0:15], v[248:251], v[236:239], v[0:15]
	v_add_f32_e32 v162, v108, v109
	v_add_f32_e32 v163, v110, v111
	v_add_f32_e32 v162, v162, v163
	v_fmac_f32_e32 v162, v215, v170
	s_setprio 0
	v_mov_b32_e32 v170, v234
	v_mov_b32_e32 v215, v162

.LBB0_212:
	v_sub_f32_e32 v64, v64, v234
	v_sub_f32_e32 v65, v65, v234
	v_sub_f32_e32 v66, v66, v234
	v_sub_f32_e32 v67, v67, v234
	v_sub_f32_e32 v68, v68, v234
	v_sub_f32_e32 v69, v69, v234
	v_sub_f32_e32 v70, v70, v234
	v_sub_f32_e32 v71, v71, v234
	v_exp_f32_e32 v64, v64
	v_exp_f32_e32 v65, v65
	v_exp_f32_e32 v66, v66
	v_exp_f32_e32 v67, v67
	v_exp_f32_e32 v68, v68
	v_exp_f32_e32 v69, v69
	v_exp_f32_e32 v70, v70
	v_exp_f32_e32 v71, v71
	v_sub_f32_e32 v72, v72, v234
	v_sub_f32_e32 v73, v73, v234
	v_sub_f32_e32 v74, v74, v234
	v_sub_f32_e32 v75, v75, v234
	v_sub_f32_e32 v76, v76, v234
	v_sub_f32_e32 v77, v77, v234
	v_sub_f32_e32 v78, v78, v234
	v_sub_f32_e32 v79, v79, v234
	s_setprio 1
	v_add_u32_e32 v163, v202, v169
	ds_read_b128 v[222:225], v163 offset:52224
	ds_read_b128 v[240:243], v163 offset:56832
	ds_read_b128 v[244:247], v163 offset:61440
	ds_read_b128 v[248:251], v207 offset:52224
	v_cvt_pk_bf16_f32 v236, v64, v65
	v_cvt_pk_bf16_f32 v237, v66, v67
	v_cvt_pk_bf16_f32 v238, v68, v69
	v_cvt_pk_bf16_f32 v239, v70, v71
	s_waitcnt lgkmcnt(3)
	s_nop 0
	v_mfma_f32_32x32x16_bf16 v[48:63], v[222:225], v[236:239], v[48:63]
	ds_read_b128 v[222:225], v163 offset:52256
	v_exp_f32_e32 v72, v72
	v_exp_f32_e32 v73, v73
	v_sub_f32_e32 v80, v80, v234
	v_sub_f32_e32 v81, v81, v234
	s_waitcnt lgkmcnt(3)
	v_mfma_f32_32x32x16_bf16 v[32:47], v[240:243], v[236:239], v[32:47]
	ds_read_b128 v[240:243], v163 offset:56864
	v_exp_f32_e32 v74, v74
	v_exp_f32_e32 v75, v75
	v_sub_f32_e32 v82, v82, v234
	v_sub_f32_e32 v83, v83, v234
	s_waitcnt lgkmcnt(3)
	v_mfma_f32_32x32x16_bf16 v[16:31], v[244:247], v[236:239], v[16:31]
	ds_read_b128 v[244:247], v163 offset:61472
	v_exp_f32_e32 v76, v76
	v_exp_f32_e32 v77, v77
	v_sub_f32_e32 v84, v84, v234
	v_sub_f32_e32 v85, v85, v234
	s_waitcnt lgkmcnt(3)
	v_mfma_f32_32x32x16_bf16 v[0:15], v[248:251], v[236:239], v[0:15]
	ds_read_b128 v[248:251], v207 offset:52256
	v_exp_f32_e32 v78, v78
	v_exp_f32_e32 v79, v79
	v_sub_f32_e32 v86, v86, v234
	v_sub_f32_e32 v87, v87, v234
	v_cvt_pk_bf16_f32 v236, v72, v73
	v_cvt_pk_bf16_f32 v237, v74, v75
	v_cvt_pk_bf16_f32 v238, v76, v77
	v_cvt_pk_bf16_f32 v239, v78, v79
	s_waitcnt lgkmcnt(3)
	s_nop 0
	v_mfma_f32_32x32x16_bf16 v[48:63], v[222:225], v[236:239], v[48:63]
	ds_read_b128 v[222:225], v163 offset:52288
	v_exp_f32_e32 v80, v80
	v_exp_f32_e32 v81, v81
	v_sub_f32_e32 v88, v88, v234
	v_sub_f32_e32 v89, v89, v234
	s_waitcnt lgkmcnt(3)
	v_mfma_f32_32x32x16_bf16 v[32:47], v[240:243], v[236:239], v[32:47]
	ds_read_b128 v[240:243], v163 offset:56896
	v_exp_f32_e32 v82, v82
	v_exp_f32_e32 v83, v83
	v_sub_f32_e32 v90, v90, v234
	v_sub_f32_e32 v91, v91, v234
	s_waitcnt lgkmcnt(3)
	v_mfma_f32_32x32x16_bf16 v[16:31], v[244:247], v[236:239], v[16:31]
	ds_read_b128 v[244:247], v163 offset:61504
	v_exp_f32_e32 v84, v84
	v_exp_f32_e32 v85, v85
	v_sub_f32_e32 v92, v92, v234
	v_sub_f32_e32 v93, v93, v234
	s_waitcnt lgkmcnt(3)
	v_mfma_f32_32x32x16_bf16 v[0:15], v[248:251], v[236:239], v[0:15]
	ds_read_b128 v[248:251], v207 offset:52288
	v_exp_f32_e32 v86, v86
	v_exp_f32_e32 v87, v87
	v_sub_f32_e32 v94, v94, v234
	v_sub_f32_e32 v95, v95, v234
	v_cvt_pk_bf16_f32 v236, v80, v81
	v_cvt_pk_bf16_f32 v237, v82, v83
	v_cvt_pk_bf16_f32 v238, v84, v85
	v_cvt_pk_bf16_f32 v239, v86, v87
	s_waitcnt lgkmcnt(3)
	s_nop 0
	v_mfma_f32_32x32x16_bf16 v[48:63], v[222:225], v[236:239], v[48:63]
	ds_read_b128 v[222:225], v163 offset:52320
	v_exp_f32_e32 v88, v88
	v_exp_f32_e32 v89, v89
	s_waitcnt lgkmcnt(3)
	v_mfma_f32_32x32x16_bf16 v[32:47], v[240:243], v[236:239], v[32:47]
	ds_read_b128 v[240:243], v163 offset:56928
	v_exp_f32_e32 v90, v90
	v_exp_f32_e32 v91, v91
	s_waitcnt lgkmcnt(3)
	v_mfma_f32_32x32x16_bf16 v[16:31], v[244:247], v[236:239], v[16:31]
	ds_read_b128 v[244:247], v163 offset:61536
	v_exp_f32_e32 v92, v92
	v_exp_f32_e32 v93, v93
	s_waitcnt lgkmcnt(3)
	v_mfma_f32_32x32x16_bf16 v[0:15], v[248:251], v[236:239], v[0:15]
	ds_read_b128 v[248:251], v207 offset:52320
	v_exp_f32_e32 v94, v94
	v_exp_f32_e32 v95, v95
	v_cvt_pk_bf16_f32 v236, v88, v89
	v_cvt_pk_bf16_f32 v237, v90, v91
	v_cvt_pk_bf16_f32 v238, v92, v93
	v_cvt_pk_bf16_f32 v239, v94, v95
	s_waitcnt lgkmcnt(3)
	s_nop 0
	v_mfma_f32_32x32x16_bf16 v[48:63], v[222:225], v[236:239], v[48:63]
	v_pk_add_f32 v[68:69], v[68:69], v[84:85]
	v_pk_add_f32 v[64:65], v[64:65], v[80:81]
	v_pk_add_f32 v[70:71], v[70:71], v[86:87]
	v_pk_add_f32 v[66:67], v[66:67], v[82:83]
	v_pk_add_f32 v[74:75], v[74:75], v[90:91]
	s_waitcnt lgkmcnt(2)
	v_mfma_f32_32x32x16_bf16 v[32:47], v[240:243], v[236:239], v[32:47]
	v_pk_add_f32 v[72:73], v[72:73], v[88:89]
	v_pk_add_f32 v[70:71], v[66:67], v[70:71]
	v_pk_add_f32 v[68:69], v[64:65], v[68:69]
	v_pk_add_f32 v[76:77], v[76:77], v[92:93]
	v_pk_add_f32 v[78:79], v[78:79], v[94:95]
	s_waitcnt lgkmcnt(1)
	v_mfma_f32_32x32x16_bf16 v[16:31], v[244:247], v[236:239], v[16:31]
	v_pk_add_f32 v[72:73], v[72:73], v[68:69]
	v_pk_add_f32 v[74:75], v[74:75], v[70:71]
	v_pk_add_f32 v[76:77], v[76:77], v[72:73]
	v_pk_add_f32 v[78:79], v[78:79], v[74:75]
	s_waitcnt lgkmcnt(0)
	v_mfma_f32_32x32x16_bf16 v[0:15], v[248:251], v[236:239], v[0:15]
	v_add_f32_e32 v162, v76, v77
	v_add_f32_e32 v163, v78, v79
	v_add_f32_e32 v162, v162, v163
	v_fmac_f32_e32 v162, v215, v170
	s_setprio 0
	v_mov_b32_e32 v170, v234
	v_mov_b32_e32 v215, v162
